# K-loop LDS-DMA loads use saddr form (SALU-maintained bases, no 64-bit VALU address adds), LDS read bases precomputed per loop entry
# speedup vs baseline: 1.0156x; 1.0156x over previous
; #define PG8_STAGE(bufoff, gbase, voff) do { _Pragma("unroll") for (int _i = 0; _i < 2; ++_i) \
;         __builtin_amdgcn_global_load_lds((const unsigned*)((const char*)(gbase) + (voff)[_i]), (LAS unsigned*)(lds + (bufoff) + ldsw + _i * 8192), 16, 0, 0); } while (0)
; #define PG8_LDA(dst, b, h) do { _Pragma("unroll") for (int m = 0; m < 4; ++m) _Pragma("unroll") for (int k = 0; k < 2; ++k) dst[m][k] = *(const LAS bf16x8*)(lds + PG8_SA(b, h) + aoff + m * 2048 + k * 1024); } while (0)
; #define PG8_LDB(dst, b, h) do { _Pragma("unroll") for (int n = 0; n < 2; ++n) _Pragma("unroll") for (int k = 0; k < 2; ++k) dst[n][k] = *(const LAS bf16x8*)(lds + PG8_SB(b, h) + boff + n * 2048 + k * 1024); } while (0)
; #define PG8_WAIT_L(n) asm volatile("s_waitcnt lgkmcnt(" #n ")" ::: "memory")
; #define PG8_BAR __builtin_amdgcn_s_barrier()
; #define PG8_SCHED __builtin_amdgcn_sched_barrier(0)
; template <class Epi>
; __device__ __forceinline__ void gemm_phase(LAS unsigned char* lds, const Gemm g, const StaticOrder& S, const Epi& E) {
;     ...
;     for (;;) {
;         const bool has_next = S.next(ui + 1, nxt);
;         const char* nA = has_next ? (const char*)g.A + (size_t)nxt.pm * tstep : cA; const char* nB = has_next ? (const char*)g.Bt + (size_t)nxt.pn * tstep : cB;
;         int t = 0;
; #pragma unroll 1
;         for (int seg = 0; seg < 3; ++seg) {
;         const int tend = (E.mode == 1) ? (seg == 0 ? 12 : (seg == 1 ? 16 : nt)) : (seg == 0 ? nt : 0);
; #pragma unroll 1
;         for (; t < tend; t += 2) {
;             const bool last = (t == nt - 2);
;             const char* a1 = cA + (size_t)(t + 1) * kstep;
;             const char* a2 = last ? nA : cA + (size_t)(t + 2) * kstep; const char* b2 = last ? nB : cB + (size_t)(t + 2) * kstep;
;             const char* a3 = a2 + kstep; const char* b3 = b2 + kstep;
;             PG8_LDB(B0, 0, 0); PG8_SCHED; PG8_LDA(At, 0, 0); PG8_STAGE(PG8_SA(1, 1), a1 + hstep, voffA);
;             PG8_WAIT_L(8); PG8_BAR; PG8_WAIT_L(0); PG8_MMA(0, 0, At, B0); PG8_BAR; PG8_SCHED;
;             PG8_LDB(B1, 0, 1); PG8_STAGE(PG8_SB(0, 0), b2, voffB);
;             PG8_BAR; PG8_WAIT_L(0); PG8_MMA(0, 1, At, B1); PG8_BAR;
;             PG8_LDA(At, 0, 1); PG8_STAGE(PG8_SA(0, 0), a2, voffA);
;             PG8_BAR; PG8_WAIT_L(0); PG8_MMA(1, 0, At, B0); PG8_BAR; PG8_SCHED;
.LBB0_204:
	s_cmp_lg_u32 s56, 1
	s_cselect_b32 s3, s7, 16
	s_cmp_eq_u32 s56, 0
	s_cselect_b32 s57, s7, 0
	s_cselect_b32 s3, 12, s3
	s_and_b64 s[46:47], s[72:73], exec
	s_cselect_b32 s57, s3, s57
	s_cmp_ge_i32 s2, s57
	s_cbranch_scc1 .LBB0_208
	s_ashr_i32 s3, s2, 31
	s_lshl_b64 s[46:47], s[2:3], 7
	s_add_u32 s3, s94, s46
	s_addc_u32 vcc_lo, s95, s47
	s_add_u32 vcc_hi, s50, s46
	s_addc_u32 s46, s51, s47
	v_add_u32_e32 v234, 0x10000, v195
	v_add_u32_e32 v235, 0x14000, v195
	v_add_u32_e32 v236, 0x18000, v195
	v_add_u32_e32 v237, 0x1c000, v195
.LBB0_206:
	s_add_i32 s78, 0, 0x10000
	ds_read_b128 v[132:135], v234
	ds_read_b128 v[136:139], v234 offset:1024
	ds_read_b128 v[140:143], v234 offset:2048
	ds_read_b128 v[144:147], v234 offset:3072
	s_add_i32 s76, s2, 1
	s_mov_b32 s47, s2
	s_add_i32 s2, s2, 2
	s_ashr_i32 s77, s76, 31
	s_cmp_eq_u32 s67, s47
	s_cselect_b32 s75, s43, s46
	s_cselect_b32 s74, s42, vcc_hi
	s_cselect_b32 s93, s63, vcc_lo
	s_cselect_b32 s92, s62, s3
	s_lshl_b64 s[76:77], s[76:77], 7
	s_add_u32 s76, s5, s76
	s_addc_u32 s77, s31, s77
	s_add_i32 m0, s11, 0xc000
	ds_read_b128 v[148:151], v200
	ds_read_b128 v[152:155], v200 offset:1024
	ds_read_b128 v[156:159], v200 offset:2048
	ds_read_b128 v[160:163], v200 offset:3072
	ds_read_b128 v[164:167], v200 offset:4096
	ds_read_b128 v[186:189], v200 offset:5120
	ds_read_b128 v[190:193], v200 offset:6144
	ds_read_b128 v[202:205], v200 offset:7168
	global_load_lds_dwordx4 v168, s[76:77]
	s_add_i32 m0, s11, 0xe000
	s_nop 0
	global_load_lds_dwordx4 v172, s[76:77]
	s_waitcnt lgkmcnt(0)
	s_barrier
	v_mfma_f32_16x16x32_bf16 v[128:131], v[132:135], v[148:151], v[128:131]
	v_mfma_f32_16x16x32_bf16 v[124:127], v[140:143], v[148:151], v[124:127]
	v_mfma_f32_16x16x32_bf16 v[112:115], v[132:135], v[156:159], v[112:115]
	v_mfma_f32_16x16x32_bf16 v[108:111], v[140:143], v[156:159], v[108:111]
	v_mfma_f32_16x16x32_bf16 v[96:99], v[132:135], v[164:167], v[96:99]
	v_mfma_f32_16x16x32_bf16 v[92:95], v[140:143], v[164:167], v[92:95]
	v_mfma_f32_16x16x32_bf16 v[80:83], v[132:135], v[190:193], v[80:83]
	v_mfma_f32_16x16x32_bf16 v[76:79], v[140:143], v[190:193], v[76:79]
	v_mfma_f32_16x16x32_bf16 v[128:131], v[136:139], v[152:155], v[128:131]
	v_mfma_f32_16x16x32_bf16 v[124:127], v[144:147], v[152:155], v[124:127]
	v_mfma_f32_16x16x32_bf16 v[112:115], v[136:139], v[160:163], v[112:115]
	v_mfma_f32_16x16x32_bf16 v[108:111], v[144:147], v[160:163], v[108:111]
	v_mfma_f32_16x16x32_bf16 v[96:99], v[136:139], v[186:189], v[96:99]
	v_mfma_f32_16x16x32_bf16 v[92:95], v[144:147], v[186:189], v[92:95]
	v_mfma_f32_16x16x32_bf16 v[80:83], v[136:139], v[202:205], v[80:83]
	v_mfma_f32_16x16x32_bf16 v[76:79], v[144:147], v[202:205], v[76:79]
	s_barrier
	s_add_i32 s47, 0, 0x14000
	s_add_i32 s76, s78, s6
	s_mov_b32 m0, s76
	ds_read_b128 v[206:209], v235
	ds_read_b128 v[222:225], v235 offset:1024
	ds_read_b128 v[226:229], v235 offset:2048
	ds_read_b128 v[230:233], v235 offset:3072
	global_load_lds_dwordx4 v170, s[92:93]
	s_add_i32 m0, s76, 0x2000
	s_nop 0
	global_load_lds_dwordx4 v174, s[92:93]
	s_waitcnt lgkmcnt(0)
	s_barrier
	v_mfma_f32_16x16x32_bf16 v[120:123], v[206:209], v[148:151], v[120:123]
	v_mfma_f32_16x16x32_bf16 v[116:119], v[226:229], v[148:151], v[116:119]
	v_mfma_f32_16x16x32_bf16 v[104:107], v[206:209], v[156:159], v[104:107]
	v_mfma_f32_16x16x32_bf16 v[100:103], v[226:229], v[156:159], v[100:103]
	v_mfma_f32_16x16x32_bf16 v[88:91], v[206:209], v[164:167], v[88:91]
	v_mfma_f32_16x16x32_bf16 v[84:87], v[226:229], v[164:167], v[84:87]
	v_mfma_f32_16x16x32_bf16 v[72:75], v[206:209], v[190:193], v[72:75]
	v_mfma_f32_16x16x32_bf16 v[68:71], v[226:229], v[190:193], v[68:71]
	v_mfma_f32_16x16x32_bf16 v[120:123], v[222:225], v[152:155], v[120:123]
	v_mfma_f32_16x16x32_bf16 v[116:119], v[230:233], v[152:155], v[116:119]
	v_mfma_f32_16x16x32_bf16 v[104:107], v[222:225], v[160:163], v[104:107]
	v_mfma_f32_16x16x32_bf16 v[100:103], v[230:233], v[160:163], v[100:103]
	v_mfma_f32_16x16x32_bf16 v[88:91], v[222:225], v[186:189], v[88:91]
	v_mfma_f32_16x16x32_bf16 v[84:87], v[230:233], v[186:189], v[84:87]
	v_mfma_f32_16x16x32_bf16 v[72:75], v[222:225], v[202:205], v[72:75]
	v_mfma_f32_16x16x32_bf16 v[68:71], v[230:233], v[202:205], v[68:71]
	s_mov_b32 m0, s11
	s_barrier
	ds_read_b128 v[148:151], v200 offset:16384
	ds_read_b128 v[152:155], v200 offset:17408
	ds_read_b128 v[156:159], v200 offset:18432
	ds_read_b128 v[160:163], v200 offset:19456
	ds_read_b128 v[164:167], v200 offset:20480
	ds_read_b128 v[186:189], v200 offset:21504
	ds_read_b128 v[190:193], v200 offset:22528
	ds_read_b128 v[202:205], v200 offset:23552
	global_load_lds_dwordx4 v168, s[74:75]
	s_mov_b32 m0, s70
	s_nop 0
	global_load_lds_dwordx4 v172, s[74:75]
	s_waitcnt lgkmcnt(0)
	s_barrier
	v_mfma_f32_16x16x32_bf16 v[64:67], v[132:135], v[148:151], v[64:67]
	v_mfma_f32_16x16x32_bf16 v[60:63], v[140:143], v[148:151], v[60:63]
	v_mfma_f32_16x16x32_bf16 v[48:51], v[132:135], v[156:159], v[48:51]
	v_mfma_f32_16x16x32_bf16 v[44:47], v[140:143], v[156:159], v[44:47]
	v_mfma_f32_16x16x32_bf16 v[32:35], v[132:135], v[164:167], v[32:35]
	v_mfma_f32_16x16x32_bf16 v[28:31], v[140:143], v[164:167], v[28:31]
	v_mfma_f32_16x16x32_bf16 v[16:19], v[132:135], v[190:193], v[16:19]
	v_mfma_f32_16x16x32_bf16 v[12:15], v[140:143], v[190:193], v[12:15]
	v_mfma_f32_16x16x32_bf16 v[64:67], v[136:139], v[152:155], v[64:67]
	v_mfma_f32_16x16x32_bf16 v[60:63], v[144:147], v[152:155], v[60:63]
	v_mfma_f32_16x16x32_bf16 v[48:51], v[136:139], v[160:163], v[48:51]
	v_mfma_f32_16x16x32_bf16 v[44:47], v[144:147], v[160:163], v[44:47]
	v_mfma_f32_16x16x32_bf16 v[32:35], v[136:139], v[186:189], v[32:35]
	v_mfma_f32_16x16x32_bf16 v[28:31], v[144:147], v[186:189], v[28:31]
	v_mfma_f32_16x16x32_bf16 v[16:19], v[136:139], v[202:205], v[16:19]
	v_mfma_f32_16x16x32_bf16 v[12:15], v[144:147], v[202:205], v[12:15]
	s_barrier
; #define PG8_STAGE(bufoff, gbase, voff) do { _Pragma("unroll") for (int _i = 0; _i < 2; ++_i) \
;         __builtin_amdgcn_global_load_lds((const unsigned*)((const char*)(gbase) + (voff)[_i]), (LAS unsigned*)(lds + (bufoff) + ldsw + _i * 8192), 16, 0, 0); } while (0)
; #define PG8_LDA(dst, b, h) do { _Pragma("unroll") for (int m = 0; m < 4; ++m) _Pragma("unroll") for (int k = 0; k < 2; ++k) dst[m][k] = *(const LAS bf16x8*)(lds + PG8_SA(b, h) + aoff + m * 2048 + k * 1024); } while (0)
; #define PG8_LDB(dst, b, h) do { _Pragma("unroll") for (int n = 0; n < 2; ++n) _Pragma("unroll") for (int k = 0; k < 2; ++k) dst[n][k] = *(const LAS bf16x8*)(lds + PG8_SB(b, h) + boff + n * 2048 + k * 1024); } while (0)
; #define PG8_MMA(ai, bj, At, Bt) do { __builtin_amdgcn_s_setprio(1); _Pragma("unroll") for (int m = 0; m < 4; ++m) _Pragma("unroll") for (int n = 0; n < 2; ++n) _Pragma("unroll") for (int k = 0; k < 2; ++k) \
;         acc[ai][bj][m][n] = __builtin_amdgcn_mfma_f32_16x16x32_bf16(Bt[n][k], At[m][k], acc[ai][bj][m][n], 0, 0, 0); __builtin_amdgcn_s_setprio(0); } while (0)
; #define PG8_WAIT_V(n) asm volatile("s_waitcnt vmcnt(" #n ")" ::: "memory")
; #define PG8_WAIT_L(n) asm volatile("s_waitcnt lgkmcnt(" #n ")" ::: "memory")
; #define PG8_BAR __builtin_amdgcn_s_barrier()
; #define PG8_SCHED __builtin_amdgcn_sched_barrier(0)
; template <class Epi>
; __device__ __forceinline__ void gemm_phase(LAS unsigned char* lds, const Gemm g, const StaticOrder& S, const Epi& E) {
;     ...
;             PG8_STAGE(PG8_SB(0, 1), b2 + hstep, voffB);
;             PG8_WAIT_V(6); PG8_BAR; PG8_MMA(1, 1, At, B1); PG8_BAR;
;             PG8_LDB(B0, 1, 0); PG8_SCHED; PG8_LDA(At, 1, 0); PG8_STAGE(PG8_SA(0, 1), a2 + hstep, voffA);
;             PG8_WAIT_L(8); PG8_BAR; PG8_WAIT_L(0); PG8_MMA(0, 0, At, B0); PG8_BAR; PG8_SCHED;
;             PG8_LDB(B1, 1, 1); PG8_STAGE(PG8_SB(1, 0), b3, voffB);
;             PG8_BAR; PG8_WAIT_L(0); PG8_MMA(0, 1, At, B1); PG8_BAR;
;             PG8_LDA(At, 1, 1); PG8_STAGE(PG8_SA(1, 0), a3, voffA);
;             PG8_BAR; PG8_WAIT_L(0); PG8_MMA(1, 0, At, B0); PG8_BAR; PG8_SCHED;
;             PG8_STAGE(PG8_SB(1, 1), b3 + hstep, voffB);
	s_add_u32 s76, s92, s13
	s_addc_u32 s77, s93, 0
	s_add_i32 s47, s47, s6
	s_mov_b32 m0, s47
	global_load_lds_dwordx4 v170, s[76:77]
	s_add_i32 m0, s47, 0x2000
	s_nop 0
	global_load_lds_dwordx4 v174, s[76:77]
	s_waitcnt vmcnt(6)
	s_barrier
	v_mfma_f32_16x16x32_bf16 v[56:59], v[206:209], v[148:151], v[56:59]
	v_mfma_f32_16x16x32_bf16 v[52:55], v[226:229], v[148:151], v[52:55]
	v_mfma_f32_16x16x32_bf16 v[40:43], v[206:209], v[156:159], v[40:43]
	v_mfma_f32_16x16x32_bf16 v[36:39], v[226:229], v[156:159], v[36:39]
	v_mfma_f32_16x16x32_bf16 v[24:27], v[206:209], v[164:167], v[24:27]
	v_mfma_f32_16x16x32_bf16 v[20:23], v[226:229], v[164:167], v[20:23]
	v_mfma_f32_16x16x32_bf16 v[8:11], v[206:209], v[190:193], v[8:11]
	v_mfma_f32_16x16x32_bf16 v[4:7], v[226:229], v[190:193], v[4:7]
	v_mfma_f32_16x16x32_bf16 v[56:59], v[222:225], v[152:155], v[56:59]
	v_mfma_f32_16x16x32_bf16 v[52:55], v[230:233], v[152:155], v[52:55]
	v_mfma_f32_16x16x32_bf16 v[40:43], v[222:225], v[160:163], v[40:43]
	v_mfma_f32_16x16x32_bf16 v[36:39], v[230:233], v[160:163], v[36:39]
	v_mfma_f32_16x16x32_bf16 v[24:27], v[222:225], v[186:189], v[24:27]
	v_mfma_f32_16x16x32_bf16 v[20:23], v[230:233], v[186:189], v[20:23]
	v_mfma_f32_16x16x32_bf16 v[8:11], v[222:225], v[202:205], v[8:11]
	v_mfma_f32_16x16x32_bf16 v[4:7], v[230:233], v[202:205], v[4:7]
	s_add_i32 s47, 0, 0x18000
	s_barrier
	ds_read_b128 v[132:135], v236
	ds_read_b128 v[136:139], v236 offset:1024
	ds_read_b128 v[140:143], v236 offset:2048
	ds_read_b128 v[144:147], v236 offset:3072
	s_add_u32 s76, s74, s13
	s_addc_u32 s77, s75, 0
	s_mov_b32 m0, s71
	ds_read_b128 v[148:151], v200 offset:32768
	ds_read_b128 v[152:155], v200 offset:33792
	ds_read_b128 v[156:159], v200 offset:34816
	ds_read_b128 v[160:163], v200 offset:35840
	ds_read_b128 v[164:167], v200 offset:36864
	ds_read_b128 v[186:189], v200 offset:37888
	ds_read_b128 v[190:193], v200 offset:38912
	ds_read_b128 v[202:205], v200 offset:39936
	global_load_lds_dwordx4 v168, s[76:77]
	s_mov_b32 m0, s19
	s_nop 0
	global_load_lds_dwordx4 v172, s[76:77]
	s_waitcnt lgkmcnt(0)
	s_barrier
	v_mfma_f32_16x16x32_bf16 v[128:131], v[132:135], v[148:151], v[128:131]
	v_mfma_f32_16x16x32_bf16 v[124:127], v[140:143], v[148:151], v[124:127]
	v_mfma_f32_16x16x32_bf16 v[112:115], v[132:135], v[156:159], v[112:115]
	v_mfma_f32_16x16x32_bf16 v[108:111], v[140:143], v[156:159], v[108:111]
	v_mfma_f32_16x16x32_bf16 v[96:99], v[132:135], v[164:167], v[96:99]
	v_mfma_f32_16x16x32_bf16 v[92:95], v[140:143], v[164:167], v[92:95]
	v_mfma_f32_16x16x32_bf16 v[80:83], v[132:135], v[190:193], v[80:83]
	v_mfma_f32_16x16x32_bf16 v[76:79], v[140:143], v[190:193], v[76:79]
	v_mfma_f32_16x16x32_bf16 v[128:131], v[136:139], v[152:155], v[128:131]
	v_mfma_f32_16x16x32_bf16 v[124:127], v[144:147], v[152:155], v[124:127]
	v_mfma_f32_16x16x32_bf16 v[112:115], v[136:139], v[160:163], v[112:115]
	v_mfma_f32_16x16x32_bf16 v[108:111], v[144:147], v[160:163], v[108:111]
	v_mfma_f32_16x16x32_bf16 v[96:99], v[136:139], v[186:189], v[96:99]
	v_mfma_f32_16x16x32_bf16 v[92:95], v[144:147], v[186:189], v[92:95]
	v_mfma_f32_16x16x32_bf16 v[80:83], v[136:139], v[202:205], v[80:83]
	v_mfma_f32_16x16x32_bf16 v[76:79], v[144:147], v[202:205], v[76:79]
	s_barrier
	s_add_i32 s47, s47, s6
	s_add_u32 s76, s92, 0x80
	s_addc_u32 s77, s93, 0
	s_mov_b32 m0, s47
	ds_read_b128 v[206:209], v237
	ds_read_b128 v[222:225], v237 offset:1024
	ds_read_b128 v[226:229], v237 offset:2048
	ds_read_b128 v[230:233], v237 offset:3072
	global_load_lds_dwordx4 v170, s[76:77]
	s_add_i32 m0, s47, 0x2000
	s_nop 0
	global_load_lds_dwordx4 v174, s[76:77]
	s_waitcnt lgkmcnt(0)
	s_barrier
; #define PG8_STAGE(bufoff, gbase, voff) do { _Pragma("unroll") for (int _i = 0; _i < 2; ++_i) \
;         __builtin_amdgcn_global_load_lds((const unsigned*)((const char*)(gbase) + (voff)[_i]), (LAS unsigned*)(lds + (bufoff) + ldsw + _i * 8192), 16, 0, 0); } while (0)
; #define PG8_LDA(dst, b, h) do { _Pragma("unroll") for (int m = 0; m < 4; ++m) _Pragma("unroll") for (int k = 0; k < 2; ++k) dst[m][k] = *(const LAS bf16x8*)(lds + PG8_SA(b, h) + aoff + m * 2048 + k * 1024); } while (0)
; #define PG8_LDB(dst, b, h) do { _Pragma("unroll") for (int n = 0; n < 2; ++n) _Pragma("unroll") for (int k = 0; k < 2; ++k) dst[n][k] = *(const LAS bf16x8*)(lds + PG8_SB(b, h) + boff + n * 2048 + k * 1024); } while (0)
; #define PG8_MMA(ai, bj, At, Bt) do { __builtin_amdgcn_s_setprio(1); _Pragma("unroll") for (int m = 0; m < 4; ++m) _Pragma("unroll") for (int n = 0; n < 2; ++n) _Pragma("unroll") for (int k = 0; k < 2; ++k) \
;         acc[ai][bj][m][n] = __builtin_amdgcn_mfma_f32_16x16x32_bf16(Bt[n][k], At[m][k], acc[ai][bj][m][n], 0, 0, 0); __builtin_amdgcn_s_setprio(0); } while (0)
; #define PG8_WAIT_V(n) asm volatile("s_waitcnt vmcnt(" #n ")" ::: "memory")
; #define PG8_WAIT_L(n) asm volatile("s_waitcnt lgkmcnt(" #n ")" ::: "memory")
; #define PG8_BAR __builtin_amdgcn_s_barrier()
; #define PG8_SCHED __builtin_amdgcn_sched_barrier(0)
; template <class Epi>
; __device__ __forceinline__ void gemm_phase(LAS unsigned char* lds, const Gemm g, const StaticOrder& S, const Epi& E) {
;     ...
;             PG8_LDB(B1, 1, 1); PG8_STAGE(PG8_SB(1, 0), b3, voffB);
;             PG8_BAR; PG8_WAIT_L(0); PG8_MMA(0, 1, At, B1); PG8_BAR;
;             PG8_LDA(At, 1, 1); PG8_STAGE(PG8_SA(1, 0), a3, voffA);
;             PG8_BAR; PG8_WAIT_L(0); PG8_MMA(1, 0, At, B0); PG8_BAR; PG8_SCHED;
;             PG8_STAGE(PG8_SB(1, 1), b3 + hstep, voffB);
;             PG8_WAIT_V(6); PG8_BAR; PG8_MMA(1, 1, At, B1); PG8_BAR;
	v_mfma_f32_16x16x32_bf16 v[120:123], v[206:209], v[148:151], v[120:123]
	v_mfma_f32_16x16x32_bf16 v[116:119], v[226:229], v[148:151], v[116:119]
	v_mfma_f32_16x16x32_bf16 v[104:107], v[206:209], v[156:159], v[104:107]
	v_mfma_f32_16x16x32_bf16 v[100:103], v[226:229], v[156:159], v[100:103]
	v_mfma_f32_16x16x32_bf16 v[88:91], v[206:209], v[164:167], v[88:91]
	v_mfma_f32_16x16x32_bf16 v[84:87], v[226:229], v[164:167], v[84:87]
	v_mfma_f32_16x16x32_bf16 v[72:75], v[206:209], v[190:193], v[72:75]
	v_mfma_f32_16x16x32_bf16 v[68:71], v[226:229], v[190:193], v[68:71]
	v_mfma_f32_16x16x32_bf16 v[120:123], v[222:225], v[152:155], v[120:123]
	v_mfma_f32_16x16x32_bf16 v[116:119], v[230:233], v[152:155], v[116:119]
	v_mfma_f32_16x16x32_bf16 v[104:107], v[222:225], v[160:163], v[104:107]
	v_mfma_f32_16x16x32_bf16 v[100:103], v[230:233], v[160:163], v[100:103]
	v_mfma_f32_16x16x32_bf16 v[88:91], v[222:225], v[186:189], v[88:91]
	v_mfma_f32_16x16x32_bf16 v[84:87], v[230:233], v[186:189], v[84:87]
	v_mfma_f32_16x16x32_bf16 v[72:75], v[222:225], v[202:205], v[72:75]
	v_mfma_f32_16x16x32_bf16 v[68:71], v[230:233], v[202:205], v[68:71]
	s_mov_b32 m0, s33
	s_add_u32 s76, s74, 0x80
	s_addc_u32 s77, s75, 0
	s_barrier
	ds_read_b128 v[148:151], v200 offset:49152
	ds_read_b128 v[152:155], v200 offset:50176
	ds_read_b128 v[156:159], v200 offset:51200
	ds_read_b128 v[160:163], v200 offset:52224
	ds_read_b128 v[164:167], v200 offset:53248
	ds_read_b128 v[186:189], v200 offset:54272
	ds_read_b128 v[190:193], v200 offset:55296
	ds_read_b128 v[202:205], v200 offset:56320
	global_load_lds_dwordx4 v168, s[76:77]
	s_mov_b32 m0, s66
	s_nop 0
	global_load_lds_dwordx4 v172, s[76:77]
	s_waitcnt lgkmcnt(0)
	s_barrier
	v_mfma_f32_16x16x32_bf16 v[64:67], v[132:135], v[148:151], v[64:67]
	v_mfma_f32_16x16x32_bf16 v[60:63], v[140:143], v[148:151], v[60:63]
	v_mfma_f32_16x16x32_bf16 v[48:51], v[132:135], v[156:159], v[48:51]
	v_mfma_f32_16x16x32_bf16 v[44:47], v[140:143], v[156:159], v[44:47]
	v_mfma_f32_16x16x32_bf16 v[32:35], v[132:135], v[164:167], v[32:35]
	v_mfma_f32_16x16x32_bf16 v[28:31], v[140:143], v[164:167], v[28:31]
	v_mfma_f32_16x16x32_bf16 v[16:19], v[132:135], v[190:193], v[16:19]
	v_mfma_f32_16x16x32_bf16 v[12:15], v[140:143], v[190:193], v[12:15]
	v_mfma_f32_16x16x32_bf16 v[64:67], v[136:139], v[152:155], v[64:67]
	v_mfma_f32_16x16x32_bf16 v[60:63], v[144:147], v[152:155], v[60:63]
	v_mfma_f32_16x16x32_bf16 v[48:51], v[136:139], v[160:163], v[48:51]
	v_mfma_f32_16x16x32_bf16 v[44:47], v[144:147], v[160:163], v[44:47]
	v_mfma_f32_16x16x32_bf16 v[32:35], v[136:139], v[186:189], v[32:35]
	v_mfma_f32_16x16x32_bf16 v[28:31], v[144:147], v[186:189], v[28:31]
	v_mfma_f32_16x16x32_bf16 v[16:19], v[136:139], v[202:205], v[16:19]
	v_mfma_f32_16x16x32_bf16 v[12:15], v[144:147], v[202:205], v[12:15]
	s_barrier
	s_add_i32 s47, s6, 0x1c000
	s_add_u32 s76, s92, s13
	s_addc_u32 s77, s93, 0
	s_add_u32 s76, s76, 0x80
	s_addc_u32 s77, s77, 0
	s_mov_b32 m0, s47
	s_nop 0
	global_load_lds_dwordx4 v170, s[76:77]
	s_add_i32 m0, s47, 0x2000
	s_nop 0
	global_load_lds_dwordx4 v174, s[76:77]
	s_waitcnt vmcnt(6)
	s_barrier
	v_mfma_f32_16x16x32_bf16 v[56:59], v[206:209], v[148:151], v[56:59]
	v_mfma_f32_16x16x32_bf16 v[52:55], v[226:229], v[148:151], v[52:55]
	v_mfma_f32_16x16x32_bf16 v[40:43], v[206:209], v[156:159], v[40:43]
	v_mfma_f32_16x16x32_bf16 v[36:39], v[226:229], v[156:159], v[36:39]
	v_mfma_f32_16x16x32_bf16 v[24:27], v[206:209], v[164:167], v[24:27]
	v_mfma_f32_16x16x32_bf16 v[20:23], v[226:229], v[164:167], v[20:23]
	v_mfma_f32_16x16x32_bf16 v[8:11], v[206:209], v[190:193], v[8:11]
	v_mfma_f32_16x16x32_bf16 v[4:7], v[226:229], v[190:193], v[4:7]
	v_mfma_f32_16x16x32_bf16 v[56:59], v[222:225], v[152:155], v[56:59]
	v_mfma_f32_16x16x32_bf16 v[52:55], v[230:233], v[152:155], v[52:55]
	v_mfma_f32_16x16x32_bf16 v[40:43], v[222:225], v[160:163], v[40:43]
	v_mfma_f32_16x16x32_bf16 v[36:39], v[230:233], v[160:163], v[36:39]
	v_mfma_f32_16x16x32_bf16 v[24:27], v[222:225], v[186:189], v[24:27]
	v_mfma_f32_16x16x32_bf16 v[20:23], v[230:233], v[186:189], v[20:23]
	v_mfma_f32_16x16x32_bf16 v[8:11], v[222:225], v[202:205], v[8:11]
	v_mfma_f32_16x16x32_bf16 v[4:7], v[230:233], v[202:205], v[4:7]
	s_add_u32 s3, s3, 0x100
	s_addc_u32 vcc_lo, vcc_lo, 0
	s_add_u32 vcc_hi, vcc_hi, 0x100
	s_addc_u32 s46, s46, 0
	s_cmp_lt_i32 s2, s57
	s_barrier
	s_cbranch_scc1 .LBB0_206
	s_movk_i32 s92, 0x90
	s_mov_b32 s93, 0x3f317217
